# dense-attn: waves 4-7 no longer raised to priority 1 (equal priority)
# speedup vs baseline: 1.0039x; 1.0039x over previous
; #define WAIT_BAR(N) asm volatile("s_waitcnt vmcnt(" #N ") lgkmcnt(0)\n\ts_barrier":::"memory")
;   #define DMA_K(t,slot) glds16(ksrc+(long)(t)*KVBLK*KP,(unsigned)__builtin_amdgcn_readfirstlane(kdst+(slot)))
;   #define DMA_V(t,slot) glds16(vsrc+(long)(t)*KVBLK*KP,(unsigned)__builtin_amdgcn_readfirstlane(vdst+(slot)))
;   #define CMASK(P0,P1,t) do{}while(0)
;   #define CMASK(P0,P1,t) do{}while(0)
;   #define CMASK(P0,P1,t) do{}while(0)
; template<int THRL> __device__ __forceinline__ void attn_unit(int b,int h,int qb,const bf16*Q,const bf16*__restrict__ K,const bf16*__restrict__ V,bf16*O,float*gssrow,float mref,char*shm){
;   int tid_l=threadIdx.x; asm volatile("":"+v"(tid_l)); const int tid=tid_l,lane=tid&63,r32=lane&31,hi=lane>>5; const int wid=__builtin_amdgcn_readfirstlane(tid>>6);
;   const long rowbase=(long)b*SEQ; const int q0=qb*QB;
;   const bf16*Qw=Q+(rowbase+q0+wid*QBLK)*QP+h*D;
;   const int g=h/3; const bf16*Kh=K+rowbase*KP+g*D,*Vh=V+rowbase*KP+g*D;
;   const unsigned lds0=(unsigned)(uintptr_t)shm;
;   float*wsf=(float*)(shm+LDS_WS)+wid*64;
;   const bf16*ksrc=Kh+(long)lane*KP+wid*8;
;   const bf16*vsrc=Vh+(long)(16*(wid&3)+(lane>>2))*KP+(wid>>2)*32+(lane&3)*8;
;   const unsigned kdst=lds0+LDS_K+wid*1024, vdst=lds0+LDS_V+wid*1024;
;     ...
;   const int vb0=(int)(lds0+LDS_V)+((lane>>4)&1)*32+(lane&3)*8+(4*hi+((lane&15)>>2))*64;
;   const char*Kbase=shm+LDS_K; bf16x8 kf[8];
;   const lds_cptr shm3=(lds_cptr)shm; const lds_cptr kp0=shm3+LDS_K+hi*1024+r32*16; const lds_cptr vp0=shm3+LDS_V+((lane>>4)&1)*32+(lane&3)*8+(4*hi+((lane&15)>>2))*64;
;   const int NT=SEQ/KVBLK;
;   DMA_K(0,0);DMA_V(0,0);DMA_K(1,SLOTB);
;   bf16x8 qr[4];
;   #pragma unroll
;   for(int d0=0;d0<4;++d0)qr[d0]=*reinterpret_cast<const bf16x8*>(&Qw[(long)r32*QP+d0*16+hi*8]);
;   float l_reg=0.f;f32x16 o[2];o[0]=f32x16{};o[1]=f32x16{};f32x16 negm;_Pragma("unroll") for(int r=0;r<16;++r)negm[r]=-mref;asm volatile("":"+v"(negm));
;     ...
;   f32x16 pA0,pA1,pB0,pB1;
;   int sl_prev=0,sl_cur=0,sl_next=SLOTB;
;     ...
;   DMA_K(2,2*SLOTB);
;   WAIT_BAR(3);
;   qkt(pA0,pA1,Kbase,qr,negm,r32,hi);asm volatile("s_nop 15\n\ts_nop 7":"+v"(pA0),"+v"(pA1));CMASK(pA0,pA1,0);
;   START(pA0,pA1);
;   _Pragma("unroll") for(int r=0;r<16;++r)pA1[r]=__builtin_amdgcn_exp2f(pA1[r]);
;   WAIT_BAR(0);
;   DMA_K(3,0);DMA_V(1,SLOTB);
;   ROT();
;   kload8(kf,kp0+sl_cur);
;   WAIT_BAR(2);
;     ...
;   if(wid>=4)__builtin_amdgcn_s_setprio(1);
.LBB0_447:
	s_bitcmp1_b32 s14, 0
	s_cselect_b32 s14, 3, 0
	v_mov_b32_e32 v194, v226
	s_add_i32 s29, s14, s5
	global_load_dword v4, v129, s[0:1]
	s_ashr_i32 s5, s4, 31
	v_readfirstlane_b32 s15, v194
	s_ashr_i32 s14, s15, 6
	s_lshl_b64 s[42:43], s[4:5], 14
	s_lshl_b32 s34, s20, 8
	s_add_u32 s20, s42, s34
	s_addc_u32 s21, s43, 0
	s_lshl_b32 s40, s14, 5
	s_ashr_i32 s41, s40, 31
	s_add_u32 s46, s20, s40
	s_addc_u32 s47, s21, s41
	s_mul_i32 s20, s47, 0x300
	s_mul_hi_u32 s21, s46, 0x300
	s_add_i32 s21, s21, s20
	s_mul_i32 s20, s46, 0x300
	v_readlane_b32 s12, v253, 57
	s_add_u32 s30, s12, s20
	v_readlane_b32 s12, v253, 58
	s_addc_u32 s31, s12, s21
	s_lshl_b32 s20, s29, 6
	s_ashr_i32 s21, s20, 31
	s_lshl_b64 s[44:45], s[20:21], 1
	s_add_u32 s20, s30, s44
	s_mul_hi_i32 s29, s29, 0x55555556
	s_addc_u32 s21, s31, s45
	s_lshr_b32 s30, s29, 31
	s_add_i32 s29, s29, s30
	s_lshl_b64 s[48:49], s[4:5], 22
	v_readlane_b32 s4, v253, 59
	s_add_u32 s30, s4, s48
	v_readlane_b32 s4, v253, 60
	s_addc_u32 s31, s4, s49
	s_lshl_b32 s4, s29, 6
	s_ashr_i32 s5, s4, 31
	s_lshl_b64 s[50:51], s[4:5], 1
	s_add_u32 s4, s30, s50
	s_addc_u32 s5, s31, s51
	v_readlane_b32 s12, v253, 61
	s_add_u32 s29, s12, s48
	v_readlane_b32 s12, v253, 62
	s_addc_u32 s31, s12, s49
	v_and_b32_e32 v195, 63, v194
	s_add_u32 s30, s29, s50
	s_addc_u32 s31, s31, s51
	v_lshlrev_b32_e32 v128, 8, v195
	s_lshl_b32 s54, s14, 3
	s_waitcnt lgkmcnt(0)
	v_lshl_add_u64 v[0:1], s[4:5], 0, v[128:129]
	s_ashr_i32 s55, s54, 31
	s_lshl_b32 s4, s14, 4
	s_waitcnt vmcnt(0)
	v_bfe_u32 v84, v194, 2, 4
	v_lshl_add_u64 v[188:189], s[54:55], 1, v[0:1]
	v_and_or_b32 v0, s4, 48, v84
	s_ashr_i32 s4, s15, 3
	s_and_b32 s52, s4, 0xffffffe0
	s_ashr_i32 s53, s52, 31
	s_lshl_b32 s5, s14, 10
	v_lshlrev_b32_e32 v0, 8, v0
	v_mov_b32_e32 v1, v129
	v_lshlrev_b32_e32 v2, 3, v194
	s_cmp_lg_u32 0, -1
	v_lshl_add_u64 v[0:1], s[30:31], 0, v[0:1]
	v_and_b32_e32 v201, 24, v2
	s_cselect_b32 s4, 0, 0
	v_lshl_add_u64 v[0:1], s[52:53], 1, v[0:1]
	v_lshlrev_b32_e32 v2, 1, v201
	v_mov_b32_e32 v3, v129
	s_add_i32 s5, s5, s4
	s_mov_b32 s29, m0
	s_mov_b32 m0, s5
	s_nop 0
	global_load_lds_dwordx4 v[188:189], off
	s_mov_b32 m0, s29
	v_and_b32_e32 v196, 31, v194
	v_lshl_add_u64 v[186:187], v[0:1], 0, v[2:3]
	s_add_i32 s4, s5, 0x6000
	s_mov_b32 s29, m0
	s_mov_b32 m0, s4
	s_nop 0
	global_load_lds_dwordx4 v[186:187], off
	s_mov_b32 m0, s29
	v_lshl_add_u64 v[0:1], v[188:189], 0, s[26:27]
	s_add_i32 s29, s5, 0x2000
	s_mov_b32 s30, m0
	s_mov_b32 m0, s29
	s_nop 0
	global_load_lds_dwordx4 v[0:1], off
	s_mov_b32 m0, s30
	v_mul_u32_u24_e32 v0, 0x180, v196
	v_bfe_u32 v197, v194, 5, 1
	v_lshlrev_b32_e32 v0, 1, v0
	v_lshl_or_b32 v2, v197, 4, v0
	global_load_dwordx4 v[158:161], v2, s[20:21]
	global_load_dwordx4 v[150:153], v2, s[20:21] offset:32
	global_load_dwordx4 v[142:145], v2, s[20:21] offset:64
	global_load_dwordx4 v[134:137], v2, s[20:21] offset:96
	s_waitcnt vmcnt(0)
	v_xor_b32_e32 v32, 0x80000000, v4
	v_lshlrev_b32_e32 v0, 10, v197
	v_lshlrev_b32_e32 v1, 4, v196
	v_mov_b32_e32 v33, v32
	v_mov_b32_e32 v34, v32
	v_mov_b32_e32 v35, v32
	v_mov_b32_e32 v36, v32
	v_mov_b32_e32 v37, v32
	v_mov_b32_e32 v38, v32
	v_mov_b32_e32 v39, v32
	v_mov_b32_e32 v40, v32
	v_mov_b32_e32 v41, v32
	v_mov_b32_e32 v42, v32
	v_mov_b32_e32 v43, v32
	v_mov_b32_e32 v44, v32
	v_mov_b32_e32 v45, v32
	v_mov_b32_e32 v46, v32
	v_mov_b32_e32 v47, v32
	v_add3_u32 v200, 0, v0, v1
	v_lshl_add_u64 v[0:1], v[188:189], 0, s[24:25]
	s_add_i32 s29, s5, 0x4000
	s_mov_b32 s20, m0
	s_mov_b32 m0, s29
	s_nop 0
	global_load_lds_dwordx4 v[0:1], off
	s_mov_b32 m0, s20
	s_waitcnt vmcnt(3) lgkmcnt(0)
	s_barrier
	ds_read_b128 v[0:3], v200
	ds_read_b128 v[48:51], v200 offset:512
	s_add_i32 s20, s5, 0x8000
	s_cmp_gt_i32 s14, 3
	s_waitcnt lgkmcnt(1)
	v_mfma_f32_32x32x16_bf16 v[16:31], v[0:3], v[158:161], v[32:47]
	s_waitcnt lgkmcnt(0)
	v_mfma_f32_32x32x16_bf16 v[0:15], v[48:51], v[158:161], v[32:47]
	ds_read_b128 v[48:51], v200 offset:2048
	ds_read_b128 v[52:55], v200 offset:2560
	s_waitcnt lgkmcnt(1)
	v_mfma_f32_32x32x16_bf16 v[16:31], v[48:51], v[150:153], v[16:31]
	s_waitcnt lgkmcnt(0)
	v_mfma_f32_32x32x16_bf16 v[0:15], v[52:55], v[150:153], v[0:15]
	ds_read_b128 v[48:51], v200 offset:4096
	ds_read_b128 v[52:55], v200 offset:4608
	s_waitcnt lgkmcnt(1)
	v_mfma_f32_32x32x16_bf16 v[16:31], v[48:51], v[142:145], v[16:31]
	s_waitcnt lgkmcnt(0)
	v_mfma_f32_32x32x16_bf16 v[0:15], v[52:55], v[142:145], v[0:15]
	ds_read_b128 v[48:51], v200 offset:6144
	ds_read_b128 v[52:55], v200 offset:6656
	s_waitcnt lgkmcnt(1)
	v_mfma_f32_32x32x16_bf16 v[16:31], v[48:51], v[134:137], v[16:31]
	v_lshl_add_u64 v[48:49], v[188:189], 0, s[22:23]
	v_lshl_add_u64 v[50:51], v[186:187], 0, s[26:27]
	s_waitcnt lgkmcnt(0)
	v_mfma_f32_32x32x16_bf16 v[0:15], v[52:55], v[134:137], v[0:15]
	s_nop 15
	s_nop 7
	s_waitcnt vmcnt(0) lgkmcnt(0)
	s_barrier
	s_mov_b32 s21, m0
	s_mov_b32 m0, s5
	s_nop 0
	global_load_lds_dwordx4 v[48:49], off
	s_mov_b32 m0, s21
	s_nop 0
	s_mov_b32 s21, m0
	s_mov_b32 m0, s20
	s_nop 0
	global_load_lds_dwordx4 v[50:51], off
	s_mov_b32 m0, s21
	ds_read_b128 v[80:83], v200 offset:8192
	ds_read_b128 v[166:169], v200 offset:8704
	ds_read_b128 v[170:173], v200 offset:10240
	ds_read_b128 v[162:165], v200 offset:10752
	ds_read_b128 v[124:127], v200 offset:12288
	ds_read_b128 v[120:123], v200 offset:12800
	ds_read_b128 v[116:119], v200 offset:14336
	ds_read_b128 v[112:115], v200 offset:14848
	s_waitcnt vmcnt(2) lgkmcnt(0)
	s_barrier
	s_cbranch_scc0 .LBB0_449
	s_setprio 0
